# gla main stage (c): six decay-vector LDS reads hoisted to the head of the stage (into otherwise unused VGPRs) instead of read-then-wait in place
# baseline (speedup 1.0000x reference)
.Lgsel_done:
	v_cndmask_b32_e64 v16, v16, 0, s[44:45]
	v_cndmask_b32_e64 v17, v17, 0, s[46:47]
	v_cndmask_b32_e64 v18, v18, 0, s[48:49]
	v_cndmask_b32_e64 v19, v19, 0, s[50:51]
	ds_write_b16 v152, v16 offset:24576
	ds_write_b16 v152, v17 offset:24656
	ds_write_b16 v152, v18 offset:24736
	ds_write_b16 v152, v19 offset:24816
	s_waitcnt lgkmcnt(0)
	s_barrier
	ds_read_b128 v[0:3], v154 offset:9216
	ds_read_b128 v[56:59], v151 offset:96
	ds_read_b128 v[4:7], v154 offset:24576
	ds_read_b128 v[28:31], v154 offset:9248
	s_waitcnt lgkmcnt(3)
	v_mfma_f32_32x32x16_bf16 v[8:23], v[0:3], v[228:231], 0
	ds_read_b128 v[162:165], v154 offset:24608
	ds_read_b128 v[166:169], v182 offset:27136
	ds_read_b128 v[64:67], v151 offset:32
	ds_read_b128 v[60:63], v151 offset:64
	ds_read_b128 v[170:173], v151
	ds_read_b128 v[0:3], v126 offset:45568
	ds_read_b128 v[200:203], v126 offset:45632
	ds_read_b128 v[204:207], v126 offset:45664
	ds_read_b128 v[248:251], v126 offset:45760
	ds_read_b128 v[158:161], v126 offset:45600
	ds_read_b128 v[184:187], v126 offset:45728
	ds_read_b128 v[196:199], v126 offset:45792
	s_waitcnt lgkmcnt(12)
	v_mfma_f32_32x32x16_bf16 v[8:23], v[28:31], v[240:243], v[8:23]
	s_waitcnt lgkmcnt(0)
	s_nop 10
	v_pk_fma_f32 v[74:75], v[74:75], v[0:1], v[8:9]
	v_pk_fma_f32 v[76:77], v[76:77], v[2:3], v[10:11]
	v_cvt_pk_bf16_f32 v0, v74, v75
	v_cvt_pk_bf16_f32 v1, v76, v77
	ds_write_b64 v109, v[0:1] offset:27136
	s_waitcnt lgkmcnt(0)
	v_pk_fma_f32 v[78:79], v[78:79], v[158:159], v[12:13]
	v_pk_fma_f32 v[80:81], v[80:81], v[160:161], v[14:15]
	v_cvt_pk_bf16_f32 v0, v78, v79
	v_cvt_pk_bf16_f32 v1, v80, v81
	ds_write_b64 v155, v[0:1] offset:27136
	ds_read_b128 v[68:71], v182 offset:27168
	v_mfma_f32_32x32x16_bf16 v[0:15], v[4:7], v[228:231], 0
	s_waitcnt lgkmcnt(1)
	v_fma_f32 v82, v82, v200, v16
	v_fma_f32 v83, v83, v201, v17
	v_fma_f32 v84, v84, v202, v18
	v_fma_f32 v85, v85, v203, v19
	v_cvt_pk_bf16_f32 v16, v82, v83
	v_cvt_pk_bf16_f32 v17, v84, v85
	ds_write_b64 v156, v[16:17] offset:27136
	v_mfma_f32_32x32x16_bf16 v[0:15], v[162:165], v[240:243], v[0:15]
	s_waitcnt lgkmcnt(0)
	v_fma_f32 v86, v86, v204, v20
	v_fma_f32 v87, v87, v205, v21
	v_fma_f32 v88, v88, v206, v22
	v_fma_f32 v89, v89, v207, v23
	v_cvt_pk_bf16_f32 v16, v86, v87
	v_cvt_pk_bf16_f32 v17, v88, v89
	ds_write_b64 v157, v[16:17] offset:27136
	ds_read_b128 v[16:19], v154 offset:11776
	ds_read_b128 v[162:165], v126 offset:45696
	s_waitcnt lgkmcnt(1)
	v_mfma_f32_32x32x16_bf16 v[16:31], v[16:19], v[228:231], 0
	ds_read_b128 v[174:177], v154 offset:11808
	ds_read_b128 v[178:181], v182 offset:27200
	s_waitcnt lgkmcnt(1)
	v_mfma_f32_32x32x16_bf16 v[16:31], v[174:177], v[240:243], v[16:31]
	v_mfma_f32_32x32x16_bf16 v[0:15], v[170:173], v[166:169], v[0:15]
	s_nop 10
	v_fma_f32 v90, v90, v162, v16
	v_fma_f32 v91, v91, v163, v17
	v_fma_f32 v92, v92, v164, v18
	v_fma_f32 v93, v93, v165, v19
	v_cvt_pk_bf16_f32 v16, v90, v91
	v_cvt_pk_bf16_f32 v17, v92, v93
	ds_write_b64 v109, v[16:17] offset:27200
	s_waitcnt lgkmcnt(0)
	v_pk_fma_f32 v[94:95], v[94:95], v[184:185], v[20:21]
	v_mfma_f32_32x32x16_bf16 v[0:15], v[64:67], v[68:71], v[0:15]
	v_fma_f32 v96, v96, v186, v22
	v_fma_f32 v97, v97, v187, v23
	v_cvt_pk_bf16_f32 v16, v94, v95
	v_cvt_pk_bf16_f32 v17, v96, v97
	ds_write_b64 v109, v[16:17] offset:27216
	ds_read_b128 v[20:23], v182 offset:27232
	s_waitcnt lgkmcnt(1)
	v_pk_fma_f32 v[98:99], v[98:99], v[248:249], v[24:25]
	v_mfma_f32_32x32x16_bf16 v[0:15], v[60:63], v[178:181], v[0:15]
	v_fma_f32 v100, v100, v250, v26
	v_fma_f32 v101, v101, v251, v27
	v_cvt_pk_bf16_f32 v16, v98, v99
	v_cvt_pk_bf16_f32 v17, v100, v101
	ds_write_b64 v109, v[16:17] offset:27232
	s_waitcnt lgkmcnt(0)
	v_pk_fma_f32 v[102:103], v[102:103], v[196:197], v[28:29]
	v_mfma_f32_32x32x16_bf16 v[0:15], v[56:59], v[20:23], v[0:15]
	v_fma_f32 v104, v104, v198, v30
	v_fma_f32 v105, v105, v199, v31
	v_cvt_pk_bf16_f32 v16, v102, v103
	v_cvt_pk_bf16_f32 v17, v104, v105
	ds_write_b64 v109, v[16:17] offset:27248
	v_add_u32_e32 v16, 0xb600, v131
	s_nop 5
	ds_write2_b32 v16, v0, v1 offset0:64 offset1:196
	v_add_u32_e32 v0, 0xba00, v131
	ds_write2_b32 v0, v2, v3 offset0:72 offset1:204
	ds_write_b32 v132, v4 offset:46848
	v_add_u32_e32 v0, 0xc800, v131
	ds_write2_b32 v0, v5, v6 offset0:100 offset1:232
	ds_write_b32 v131, v7 offset:52656
	ds_write_b32 v133, v8 offset:46848
	v_add_u32_e32 v0, 0xda00, v131
	ds_write2_b32 v0, v9, v10 offset0:4 offset1:136
	ds_write_b32 v131, v11 offset:56880
	ds_write_b32 v134, v12 offset:46848
	v_add_u32_e32 v0, 0xea00, v131
	ds_write2_b32 v0, v13, v14 offset0:36 offset1:168
	ds_write_b32 v131, v15 offset:61104
	s_waitcnt lgkmcnt(0)
	s_barrier
	v_lshl_add_u32 v16, s2, 5, v127
	ds_read_b128 v[0:3], v128 offset:46848
	ds_read_b128 v[4:7], v128 offset:46864
	ds_read_b128 v[8:11], v128 offset:46880
	ds_read_b128 v[12:15], v128 offset:46896
	v_ashrrev_i32_e32 v17, 31, v16
	v_lshl_add_u64 v[16:17], v[16:17], 0, s[12:13]
	v_lshlrev_b64 v[16:17], 10, v[16:17]
	v_lshl_add_u64 v[16:17], v[118:119], 0, v[16:17]
	s_waitcnt lgkmcnt(3)
	v_cvt_pk_bf16_f32 v0, v0, v1
	v_cvt_pk_bf16_f32 v1, v2, v3
	s_waitcnt lgkmcnt(2)
	v_cvt_pk_bf16_f32 v2, v4, v5
	v_cvt_pk_bf16_f32 v3, v6, v7
	global_store_dwordx4 v[16:17], v[0:3], off
	s_waitcnt lgkmcnt(1)
	s_nop 0
	v_cvt_pk_bf16_f32 v0, v8, v9
	v_cvt_pk_bf16_f32 v1, v10, v11
	s_waitcnt lgkmcnt(0)
	v_cvt_pk_bf16_f32 v2, v12, v13
	v_cvt_pk_bf16_f32 v3, v14, v15
	global_store_dwordx4 v[16:17], v[0:3], off offset:16
	s_cbranch_scc1 .LBB0_643
